# all 10 grid barriers XCD-local (spin-complete census check before the one global sync, global fallback), transients re-based per XCD, redundant acc zeroing removed, no setprio
# speedup vs baseline: 1.0272x; 1.0105x over previous
.LBB0_128:
	s_or_b64 exec, exec, s[0:1]
	s_lshl_b32 s98, s3, 8
	s_add_i32 s98, s98, 0x400
	v_mov_b32_e32 v2, s98
	s_lshr_b32 s99, s72, 3
	s_mov_b32 s100, 0
.Lcen_spin:
	global_load_dword v1, v2, s[38:39] sc1
	s_waitcnt vmcnt(0)
	v_readfirstlane_b32 s98, v1
	s_nop 3
	s_cmp_ge_u32 s98, s99
	s_cbranch_scc1 .Lcen_done
	s_sleep 8
	s_add_u32 s100, s100, 1
	s_cmp_lt_u32 s100, 0x20000
	s_cbranch_scc1 .Lcen_spin
.Lcen_done:
	s_lshl_b32 s98, s3, 2
	s_add_i32 s98, s98, 0x3700
	v_mov_b32_e32 v1, s98
	s_lshl_b32 s98, s3, 8
	s_add_i32 s98, s98, 0x400
	v_mov_b32_e32 v2, s98
	global_load_dword v1, v1, s[38:39] sc1
	global_load_dword v2, v2, s[38:39] sc1
	s_and_b32 s98, s2, 7
	s_lshl_b32 s98, 1, s98
	s_lshr_b32 s99, s72, 3
	s_waitcnt vmcnt(0)
	v_cmp_ne_u32_e32 vcc, s98, v1
	v_cmp_ne_u32_e64 s[100:101], s99, v2
	s_nop 3
	s_or_b64 vcc, vcc, s[100:101]
	s_cbranch_vccz .Lcensus_ok
	v_mov_b32_e32 v1, 0x3780
	v_mov_b32_e32 v2, 1
	global_atomic_or v1, v2, s[38:39]
.Lcensus_ok:
	s_mov_b32 s101, 0
	v_lshrrev_b32_e32 v1, 20, v0
	v_lshrrev_b32_e32 v0, 10, v0
	v_or_b32_e32 v0, v0, v1
	s_movk_i32 s0, 0x3ff
	v_and_or_b32 v0, v0, s0, v218
	v_cmp_eq_u32_e32 vcc, 0, v0
	s_waitcnt lgkmcnt(0)
	s_barrier
	s_and_saveexec_b64 s[0:1], vcc
	s_cbranch_execz .LBB0_138
	buffer_wbl2 sc1
	s_waitcnt vmcnt(0)
	s_load_dwordx2 s[4:5], s[20:21], 0x58
	v_mov_b32_e32 v2, 0
	s_mov_b64 s[6:7], exec
	v_mbcnt_lo_u32_b32 v1, s6, 0
	v_mbcnt_hi_u32_b32 v1, s7, v1
	s_waitcnt lgkmcnt(0)
	global_load_dword v0, v2, s[4:5] offset:40
	v_cmp_eq_u32_e32 vcc, 0, v1
	s_and_saveexec_b64 s[8:9], vcc
	s_cbranch_execz .LBB0_131
	s_bcnt1_i32_b64 s6, s[6:7]
	v_mov_b32_e32 v3, s6
	global_atomic_add v3, v2, v3, s[4:5] offset:32 sc0

.LBB0_138:
	s_or_b64 exec, exec, s[0:1]
	v_mov_b32_e32 v1, 0x3780
	global_load_dword v1, v1, s[38:39] sc1
	s_waitcnt vmcnt(0)
	v_readfirstlane_b32 s98, v1
	s_nop 3
	s_cmp_eq_u32 s98, 0
	s_cselect_b32 s101, 1, 0
	s_cmpk_lt_i32 s2, 0x200
	s_cselect_b64 s[4:5], -1, 0
	v_writelane_b32 v253, s4, 50
	s_lshl_b32 s1, s2, 6
	s_and_b32 s1, s1, 0x1c0
	v_writelane_b32 v253, s5, 51
	s_ashr_i32 s4, s2, 3
	s_add_i32 s1, s1, s4
	s_ashr_i32 s5, s1, 2
	s_lshl_b32 s1, s4, 1
	s_and_b32 s1, s1, 6
	v_writelane_b32 v253, s1, 52
	s_ashr_i32 s1, s5, 31
	s_add_u32 s68, s26, 0x280200
	s_addc_u32 s69, s27, 0
	s_add_u32 s70, s26, 0x280400
	s_addc_u32 s71, s27, 0
	s_add_u32 s66, s26, 0x280500
	s_addc_u32 s67, s27, 0
	s_add_u32 s34, s26, 0x280600
	s_addc_u32 s35, s27, 0
	s_add_u32 s36, s26, 0x280700
	s_addc_u32 s37, s27, 0
	s_add_u32 s56, s26, 0x280800
	s_addc_u32 s57, s27, 0
	s_add_u32 s58, s26, 0x280900
	s_addc_u32 s59, s27, 0
	s_add_u32 s60, s26, 0x280a00
	s_addc_u32 s61, s27, 0
	s_add_u32 s76, s26, 0x280b00
	s_addc_u32 s77, s27, 0
	s_add_u32 s78, s26, 0x280c00
	s_addc_u32 s79, s27, 0
	s_add_u32 s80, s26, 0x280d00
	s_addc_u32 s81, s27, 0
	s_add_u32 s82, s26, 0x280e00
	s_addc_u32 s83, s27, 0
	s_add_u32 s84, s26, 0x280f00
	s_addc_u32 s85, s27, 0
	s_add_u32 s86, s26, 0x281000
	s_addc_u32 s87, s27, 0
	s_add_u32 s88, s26, 0x281100
	s_addc_u32 s89, s27, 0
	s_add_u32 s90, s26, 0x281200
	s_addc_u32 s91, s27, 0
	s_add_u32 s92, s26, 0x281300
	s_addc_u32 s93, s27, 0
	s_mul_i32 s0, s73, s72
	v_writelane_b32 v253, s5, 54
	s_cmp_eq_u32 s3, 15
	v_writelane_b32 v253, s1, 56
	s_mul_i32 s94, s0, s33
	s_cselect_b64 s[0:1], -1, 0
	v_writelane_b32 v253, s0, 58
	s_cmp_eq_u32 s3, 14
	s_movk_i32 s53, 0x161
	v_writelane_b32 v253, s1, 59
	s_cselect_b64 s[0:1], -1, 0
	v_writelane_b32 v253, s0, 60
	s_cmp_eq_u32 s3, 13
	v_mov_b32_e32 v177, 0
	v_writelane_b32 v253, s1, 61
	s_cselect_b64 s[0:1], -1, 0
	v_writelane_b32 v253, s0, 62
	s_cmp_eq_u32 s3, 12
	v_mov_b32_e32 v220, 0x358637bd
	v_writelane_b32 v253, s1, 63
	s_cselect_b64 s[0:1], -1, 0
	v_writelane_b32 v254, s0, 0
	s_cmp_eq_u32 s3, 11
	v_writelane_b32 v253, s60, 16
	v_writelane_b32 v254, s1, 1
	s_cselect_b64 s[0:1], -1, 0
	v_writelane_b32 v254, s0, 2
	s_cmp_eq_u32 s3, 10
	v_mov_b32_e32 v221, 1
	v_writelane_b32 v254, s1, 3
	s_cselect_b64 s[0:1], -1, 0
	v_writelane_b32 v254, s0, 4
	s_cmp_eq_u32 s3, 9
	v_mbcnt_hi_u32_b32 v219, -1, v51
	v_writelane_b32 v254, s1, 5
	s_cselect_b64 s[0:1], -1, 0
	v_writelane_b32 v254, s0, 6
	s_cmp_eq_u32 s3, 8
	v_mov_b64_e32 v[178:179], 0x1ff
	v_writelane_b32 v254, s1, 7
	s_cselect_b64 s[0:1], -1, 0
	v_writelane_b32 v254, s0, 8
	s_cmp_eq_u32 s3, 7
	v_mov_b64_e32 v[180:181], 0x200
	v_writelane_b32 v254, s1, 9
	s_cselect_b64 s[0:1], -1, 0
	v_writelane_b32 v254, s0, 10
	s_cmp_eq_u32 s3, 6
	v_mov_b64_e32 v[182:183], 0xb00
	v_writelane_b32 v254, s1, 11
	s_cselect_b64 s[0:1], -1, 0
	v_writelane_b32 v254, s0, 12
	s_cmp_eq_u32 s3, 5
	v_mov_b64_e32 v[184:185], 0xaff
	v_writelane_b32 v254, s1, 13
	s_cselect_b64 s[0:1], -1, 0
	v_writelane_b32 v254, s0, 14
	s_cmp_eq_u32 s3, 4
	s_mov_b32 s17, 0
	v_writelane_b32 v254, s1, 15
	s_cselect_b64 s[0:1], -1, 0
	v_writelane_b32 v254, s0, 16
	s_cmp_eq_u32 s3, 3
	s_mov_b64 s[14:15], 0x80
	v_writelane_b32 v254, s1, 17
	s_cselect_b64 s[0:1], -1, 0
	v_writelane_b32 v254, s0, 18
	s_cmp_eq_u32 s3, 2
	v_writelane_b32 v253, s61, 17
	v_writelane_b32 v254, s1, 19
	s_cselect_b64 s[0:1], -1, 0
	v_writelane_b32 v254, s0, 20
	s_cmp_eq_u32 s3, 1
	s_barrier
	v_writelane_b32 v254, s1, 21
	s_cselect_b64 s[0:1], -1, 0
	v_writelane_b32 v254, s0, 22
	s_cmp_eq_u32 s3, 0
	s_nop 0
	v_writelane_b32 v254, s1, 23
	s_cselect_b64 s[0:1], -1, 0
	v_writelane_b32 v254, s0, 24
	s_nop 1
	v_writelane_b32 v254, s1, 25
	s_lshl_b32 s0, s3, 8
	s_add_u32 s0, s38, s0
	s_addc_u32 s1, s39, 0
	s_add_u32 s4, s0, 0x1400
	s_addc_u32 s5, s1, 0
	v_writelane_b32 v254, s4, 26
	s_add_u32 s0, s0, 0x2400
	s_addc_u32 s1, s1, 0
	v_writelane_b32 v254, s5, 27
	v_writelane_b32 v254, s0, 28
	s_nop 1
	v_writelane_b32 v254, s1, 29
	s_add_u32 s0, s26, 0x283400
	s_addc_u32 s1, s27, 0
	v_writelane_b32 v254, s0, 30
	s_nop 1
	v_writelane_b32 v254, s1, 31
	s_add_u32 s0, s26, 0x283500
	s_addc_u32 s1, s27, 0
	v_writelane_b32 v254, s0, 32
	s_ashr_i32 s3, s2, 31
	s_ashr_i32 s73, s72, 31
	v_writelane_b32 v254, s1, 33
	s_lshr_b32 s0, s3, 29
	s_add_i32 s0, s2, s0
	s_ashr_i32 s7, s0, 3
	s_and_b32 s0, s0, -8
	s_sub_i32 s8, s2, s0
	s_cmp_gt_i32 s8, -1
	s_cselect_b64 s[0:1], -1, 0
	s_lshl_b32 s4, s8, 6
	v_writelane_b32 v254, s0, 34
	s_cmpk_lt_i32 s2, 0xb00
	s_nop 0
	v_writelane_b32 v254, s1, 35
	s_cselect_b64 s[0:1], -1, 0
	v_writelane_b32 v254, s0, 36
	s_cmp_lt_i32 s8, 0
	s_nop 0
	v_writelane_b32 v254, s1, 37
	s_cselect_b64 s[0:1], -1, 0
	v_writelane_b32 v254, s0, 38
	s_nop 1
	v_writelane_b32 v254, s1, 39
	s_and_b64 s[0:1], s[0:1], exec
	s_mul_i32 s0, s8, 0x41
	s_cselect_b32 s0, s0, s4
	s_cselect_b32 s1, s53, 0x160
	s_add_i32 s5, s0, s7
	s_ashr_i32 s0, s5, 31
	v_writelane_b32 v254, s0, 40
	s_lshr_b32 s0, s0, 27
	s_add_i32 s0, s5, s0
	s_and_b32 s4, s0, 0xffe0
	s_sub_i32 s4, s5, s4
	v_writelane_b32 v254, s5, 42
	s_bfe_i32 s5, s4, 0x80000
	s_bfe_u32 s5, s5, 0x3000c
	s_add_i32 s5, s4, s5
	s_and_b32 s6, s5, 0xf8
	s_sub_i32 s4, s4, s6
	s_ashr_i32 s0, s0, 5
	s_lshl_b32 s0, s0, 3
	s_sext_i32_i8 s4, s4
	s_add_i32 s95, s0, s4
	s_mul_i32 s0, s8, s1
	s_add_i32 s0, s0, s7
	s_mul_hi_i32 s1, s0, 0x2e8ba2e9
	s_lshr_b32 s4, s1, 31
	s_ashr_i32 s1, s1, 5
	s_add_i32 s1, s1, s4
	s_mul_i32 s4, s1, 0xb0
	s_sub_i32 s0, s0, s4
	s_bfe_u32 s4, s0, 0x3001c
	s_add_i32 s4, s0, s4
	s_and_b32 s6, s4, 0xfff8
	s_sub_i32 s0, s0, s6
	s_lshl_b32 s1, s1, 3
	s_sext_i32_i16 s0, s0
	v_writelane_b32 v254, s8, 44
	s_add_i32 s8, s1, s0
	s_bfe_i32 s0, s5, 0x80000
	s_sext_i32_i16 s1, s0
	s_sext_i32_i16 s0, s4
	v_writelane_b32 v254, s7, 45
	s_ashr_i32 s4, s0, 3
	s_lshr_b32 s0, s0, 3
	v_writelane_b32 v254, s4, 46
	s_bfe_i64 s[4:5], s[0:1], 0x100000
	v_writelane_b32 v254, s4, 47
	s_ashr_i32 s0, s1, 3
	s_mov_b64 s[6:7], -1
	v_writelane_b32 v254, s5, 48
	v_writelane_b32 v254, s0, 49
	s_lshr_b32 s0, s1, 3
	s_bfe_i64 s[0:1], s[0:1], 0x100000
	v_writelane_b32 v254, s0, 50
	s_nop 1
	v_writelane_b32 v254, s1, 51
	s_ashr_i32 s0, s8, 31
	v_writelane_b32 v254, s0, 52
	s_ashr_i32 s0, s95, 31
	v_writelane_b32 v254, s0, 53
	s_add_i32 s0, 0, 0x20000
	v_writelane_b32 v254, s0, 54
	s_add_i32 s0, 0, 0x20004
	v_writelane_b32 v254, s0, 55
	v_writelane_b32 v254, s94, 56
	v_writelane_b32 v254, s68, 57
	s_mov_b32 s0, 0
	s_nop 0
	v_writelane_b32 v254, s69, 58
	v_writelane_b32 v254, s70, 59
	s_nop 1
	v_writelane_b32 v254, s71, 60
	v_writelane_b32 v254, s66, 61
	s_nop 1
	v_writelane_b32 v254, s67, 62
	v_writelane_b32 v254, s34, 63
	s_nop 1
	v_writelane_b32 v255, s35, 0
	v_writelane_b32 v255, s56, 1
	s_nop 1
	v_writelane_b32 v255, s57, 2
	v_writelane_b32 v255, s58, 3
	s_nop 1
	v_writelane_b32 v255, s59, 4
	v_writelane_b32 v255, s95, 5
	v_writelane_b32 v255, s8, 6
	v_writelane_b32 v255, s36, 7
	s_nop 1
	v_writelane_b32 v255, s37, 8
	s_branch .LBB0_141

.LBB0_153:
	v_mov_b32_e32 v123, 0
	s_andn2_b64 vcc, exec, s[36:37]
	v_mov_b32_e32 v122, v123
	v_mov_b32_e32 v121, v123
	v_mov_b32_e32 v120, v123
	v_mov_b32_e32 v119, v123
	v_mov_b32_e32 v118, v123
	v_mov_b32_e32 v117, v123
	v_mov_b32_e32 v116, v123
	v_mov_b32_e32 v111, v123
	v_mov_b32_e32 v110, v123
	v_mov_b32_e32 v109, v123
	v_mov_b32_e32 v108, v123
	v_mov_b32_e32 v103, v123
	v_mov_b32_e32 v102, v123
	v_mov_b32_e32 v101, v123
	v_mov_b32_e32 v100, v123
	v_mov_b32_e32 v95, v123
	v_mov_b32_e32 v94, v123
	v_mov_b32_e32 v93, v123
	v_mov_b32_e32 v92, v123
	v_mov_b32_e32 v87, v123
	v_mov_b32_e32 v86, v123
	v_mov_b32_e32 v85, v123
	v_mov_b32_e32 v84, v123
	v_mov_b32_e32 v79, v123
	v_mov_b32_e32 v78, v123
	v_mov_b32_e32 v77, v123
	v_mov_b32_e32 v76, v123
	v_mov_b32_e32 v71, v123
	v_mov_b32_e32 v70, v123
	v_mov_b32_e32 v69, v123
	v_mov_b32_e32 v68, v123
	v_mov_b32_e32 v127, v123
	v_mov_b32_e32 v126, v123
	v_mov_b32_e32 v125, v123
	v_mov_b32_e32 v124, v123
	v_mov_b32_e32 v115, v123
	v_mov_b32_e32 v114, v123
	v_mov_b32_e32 v113, v123
	v_mov_b32_e32 v112, v123
	v_mov_b32_e32 v107, v123
	v_mov_b32_e32 v106, v123
	v_mov_b32_e32 v105, v123
	v_mov_b32_e32 v104, v123
	v_mov_b32_e32 v99, v123
	v_mov_b32_e32 v98, v123
	v_mov_b32_e32 v97, v123
	v_mov_b32_e32 v96, v123
	v_mov_b32_e32 v91, v123
	v_mov_b32_e32 v90, v123
	v_mov_b32_e32 v89, v123
	v_mov_b32_e32 v88, v123
	v_mov_b32_e32 v83, v123
	v_mov_b32_e32 v82, v123
	v_mov_b32_e32 v81, v123
	v_mov_b32_e32 v80, v123
	v_mov_b32_e32 v75, v123
	v_mov_b32_e32 v74, v123
	v_mov_b32_e32 v73, v123
	v_mov_b32_e32 v72, v123
	v_mov_b32_e32 v67, v123
	v_mov_b32_e32 v66, v123
	v_mov_b32_e32 v65, v123
	v_mov_b32_e32 v64, v123
	v_mov_b32_e32 v63, v123
	v_mov_b32_e32 v62, v123
	v_mov_b32_e32 v61, v123
	v_mov_b32_e32 v60, v123
	v_mov_b32_e32 v55, v123
	v_mov_b32_e32 v54, v123
	v_mov_b32_e32 v53, v123
	v_mov_b32_e32 v52, v123
	v_mov_b32_e32 v47, v123
	v_mov_b32_e32 v46, v123
	v_mov_b32_e32 v45, v123
	v_mov_b32_e32 v44, v123
	v_mov_b32_e32 v39, v123
	v_mov_b32_e32 v38, v123
	v_mov_b32_e32 v37, v123
	v_mov_b32_e32 v36, v123
	v_mov_b32_e32 v31, v123
	v_mov_b32_e32 v30, v123
	v_mov_b32_e32 v29, v123
	v_mov_b32_e32 v28, v123
	v_mov_b32_e32 v23, v123
	v_mov_b32_e32 v22, v123
	v_mov_b32_e32 v21, v123
	v_mov_b32_e32 v20, v123
	v_mov_b32_e32 v15, v123
	v_mov_b32_e32 v14, v123
	v_mov_b32_e32 v13, v123
	v_mov_b32_e32 v12, v123
	v_mov_b32_e32 v7, v123
	v_mov_b32_e32 v6, v123
	v_mov_b32_e32 v5, v123
	v_mov_b32_e32 v4, v123
	v_mov_b32_e32 v59, v123
	v_mov_b32_e32 v58, v123
	v_mov_b32_e32 v57, v123
	v_mov_b32_e32 v56, v123
	v_mov_b32_e32 v51, v123
	v_mov_b32_e32 v50, v123
	v_mov_b32_e32 v49, v123
	v_mov_b32_e32 v48, v123
	v_mov_b32_e32 v43, v123
	v_mov_b32_e32 v42, v123
	v_mov_b32_e32 v41, v123
	v_mov_b32_e32 v40, v123
	v_mov_b32_e32 v35, v123
	v_mov_b32_e32 v34, v123
	v_mov_b32_e32 v33, v123
	v_mov_b32_e32 v32, v123
	v_mov_b32_e32 v27, v123
	v_mov_b32_e32 v26, v123
	v_mov_b32_e32 v25, v123
	v_mov_b32_e32 v24, v123
	v_mov_b32_e32 v19, v123
	v_mov_b32_e32 v18, v123
	v_mov_b32_e32 v17, v123
	v_mov_b32_e32 v16, v123
	v_mov_b32_e32 v11, v123
	v_mov_b32_e32 v10, v123
	v_mov_b32_e32 v9, v123
	v_mov_b32_e32 v8, v123
	v_mov_b32_e32 v3, v123
	v_mov_b32_e32 v2, v123
	v_mov_b32_e32 v1, v123
	v_mov_b32_e32 v0, v123
	s_cbranch_vccnz .LBB0_156
	s_add_u32 s42, s42, 0x80
	s_addc_u32 s43, s43, 0
	s_add_u32 s10, s44, 0x100
	s_addc_u32 s11, s45, 0
	s_mov_b32 s44, 0

.LBB0_230:
	s_or_b64 exec, exec, s[0:1]
	v_readlane_b32 s56, v253, 32
	s_xor_b64 s[0:1], s[6:7], -1
	v_readlane_b32 s70, v253, 46
	v_readlane_b32 s71, v253, 47
	v_writelane_b32 v255, s0, 18
	s_mov_b64 s[6:7], s[70:71]
	s_waitcnt lgkmcnt(0)
	v_writelane_b32 v255, s1, 19
	s_barrier
	s_add_u32 s8, s6, 0x12d00000
	v_mov_b32_e32 v24, v218
	s_movk_i32 s0, 0x100
	s_addc_u32 s9, s7, 0
	s_and_b32 s98, s2, 7
	s_mul_i32 s98, s98, 0xe00000
	s_add_u32 s8, s8, s98
	s_addc_u32 s9, s9, 0
	v_readlane_b32 s57, v253, 33
	v_cmp_gt_i32_e32 vcc, s0, v24
	v_readlane_b32 s58, v253, 34
	v_readlane_b32 s59, v253, 35
	v_readlane_b32 s60, v253, 36
	v_readlane_b32 s61, v253, 37
	v_readlane_b32 s62, v253, 38
	v_readlane_b32 s63, v253, 39
	v_readlane_b32 s64, v253, 40
	v_readlane_b32 s65, v253, 41
	v_readlane_b32 s66, v253, 42
	v_readlane_b32 s67, v253, 43
	v_readlane_b32 s68, v253, 44
	v_readlane_b32 s69, v253, 45
	s_and_saveexec_b64 s[0:1], vcc
	s_xor_b64 s[0:1], exec, s[0:1]
	s_cbranch_execz .LBB0_243
	v_lshlrev_b32_e32 v0, 3, v24
	v_and_b32_e32 v32, 0x3f8, v0
	v_lshlrev_b32_e32 v20, 2, v32
	global_load_dwordx4 v[0:3], v20, s[22:23] offset:16
	global_load_dwordx4 v[4:7], v20, s[22:23]
	global_load_dwordx4 v[8:11], v20, s[20:21] offset:16
	global_load_dwordx4 v[12:15], v20, s[20:21]
	global_load_dwordx4 v[16:19], v20, s[18:19] offset:16
	s_nop 0
	global_load_dwordx4 v[20:23], v20, s[18:19]
	s_add_u32 s12, s6, 0xa900000
	s_addc_u32 s13, s7, 0
	s_add_u32 s18, s6, 0xe900000
	s_addc_u32 s19, s7, 0
	v_ashrrev_i32_e32 v33, 7, v24
	s_mov_b64 s[20:21], s[2:3]
	s_branch .LBB0_234

.LBB0_260:
	v_mov_b32_e32 v123, 0
	s_andn2_b64 vcc, exec, s[22:23]
	v_mov_b32_e32 v122, v123
	v_mov_b32_e32 v121, v123
	v_mov_b32_e32 v120, v123
	v_mov_b32_e32 v127, v123
	v_mov_b32_e32 v126, v123
	v_mov_b32_e32 v125, v123
	v_mov_b32_e32 v124, v123
	v_mov_b32_e32 v111, v123
	v_mov_b32_e32 v110, v123
	v_mov_b32_e32 v109, v123
	v_mov_b32_e32 v108, v123
	v_mov_b32_e32 v107, v123
	v_mov_b32_e32 v106, v123
	v_mov_b32_e32 v105, v123
	v_mov_b32_e32 v104, v123
	v_mov_b32_e32 v95, v123
	v_mov_b32_e32 v94, v123
	v_mov_b32_e32 v93, v123
	v_mov_b32_e32 v92, v123
	v_mov_b32_e32 v91, v123
	v_mov_b32_e32 v90, v123
	v_mov_b32_e32 v89, v123
	v_mov_b32_e32 v88, v123
	v_mov_b32_e32 v79, v123
	v_mov_b32_e32 v78, v123
	v_mov_b32_e32 v77, v123
	v_mov_b32_e32 v76, v123
	v_mov_b32_e32 v75, v123
	v_mov_b32_e32 v74, v123
	v_mov_b32_e32 v73, v123
	v_mov_b32_e32 v72, v123
	v_mov_b32_e32 v119, v123
	v_mov_b32_e32 v118, v123
	v_mov_b32_e32 v117, v123
	v_mov_b32_e32 v116, v123
	v_mov_b32_e32 v115, v123
	v_mov_b32_e32 v114, v123
	v_mov_b32_e32 v113, v123
	v_mov_b32_e32 v112, v123
	v_mov_b32_e32 v103, v123
	v_mov_b32_e32 v102, v123
	v_mov_b32_e32 v101, v123
	v_mov_b32_e32 v100, v123
	v_mov_b32_e32 v99, v123
	v_mov_b32_e32 v98, v123
	v_mov_b32_e32 v97, v123
	v_mov_b32_e32 v96, v123
	v_mov_b32_e32 v87, v123
	v_mov_b32_e32 v86, v123
	v_mov_b32_e32 v85, v123
	v_mov_b32_e32 v84, v123
	v_mov_b32_e32 v83, v123
	v_mov_b32_e32 v82, v123
	v_mov_b32_e32 v81, v123
	v_mov_b32_e32 v80, v123
	v_mov_b32_e32 v71, v123
	v_mov_b32_e32 v70, v123
	v_mov_b32_e32 v69, v123
	v_mov_b32_e32 v68, v123
	v_mov_b32_e32 v67, v123
	v_mov_b32_e32 v66, v123
	v_mov_b32_e32 v65, v123
	v_mov_b32_e32 v64, v123
	v_mov_b32_e32 v63, v123
	v_mov_b32_e32 v62, v123
	v_mov_b32_e32 v61, v123
	v_mov_b32_e32 v60, v123
	v_mov_b32_e32 v59, v123
	v_mov_b32_e32 v58, v123
	v_mov_b32_e32 v57, v123
	v_mov_b32_e32 v56, v123
	v_mov_b32_e32 v47, v123
	v_mov_b32_e32 v46, v123
	v_mov_b32_e32 v45, v123
	v_mov_b32_e32 v44, v123
	v_mov_b32_e32 v43, v123
	v_mov_b32_e32 v42, v123
	v_mov_b32_e32 v41, v123
	v_mov_b32_e32 v40, v123
	v_mov_b32_e32 v31, v123
	v_mov_b32_e32 v30, v123
	v_mov_b32_e32 v29, v123
	v_mov_b32_e32 v28, v123
	v_mov_b32_e32 v27, v123
	v_mov_b32_e32 v26, v123
	v_mov_b32_e32 v25, v123
	v_mov_b32_e32 v24, v123
	v_mov_b32_e32 v15, v123
	v_mov_b32_e32 v14, v123
	v_mov_b32_e32 v13, v123
	v_mov_b32_e32 v12, v123
	v_mov_b32_e32 v11, v123
	v_mov_b32_e32 v10, v123
	v_mov_b32_e32 v9, v123
	v_mov_b32_e32 v8, v123
	v_mov_b32_e32 v55, v123
	v_mov_b32_e32 v54, v123
	v_mov_b32_e32 v53, v123
	v_mov_b32_e32 v52, v123
	v_mov_b32_e32 v51, v123
	v_mov_b32_e32 v50, v123
	v_mov_b32_e32 v49, v123
	v_mov_b32_e32 v48, v123
	v_mov_b32_e32 v39, v123
	v_mov_b32_e32 v38, v123
	v_mov_b32_e32 v37, v123
	v_mov_b32_e32 v36, v123
	v_mov_b32_e32 v35, v123
	v_mov_b32_e32 v34, v123
	v_mov_b32_e32 v33, v123
	v_mov_b32_e32 v32, v123
	v_mov_b32_e32 v23, v123
	v_mov_b32_e32 v22, v123
	v_mov_b32_e32 v21, v123
	v_mov_b32_e32 v20, v123
	v_mov_b32_e32 v19, v123
	v_mov_b32_e32 v18, v123
	v_mov_b32_e32 v17, v123
	v_mov_b32_e32 v16, v123
	v_mov_b32_e32 v7, v123
	v_mov_b32_e32 v6, v123
	v_mov_b32_e32 v5, v123
	v_mov_b32_e32 v4, v123
	v_mov_b32_e32 v3, v123
	v_mov_b32_e32 v2, v123
	s_waitcnt lgkmcnt(0)
	v_mov_b32_e32 v1, v123
	v_mov_b32_e32 v0, v123
	s_cbranch_vccnz .LBB0_263
	s_add_u32 s30, s30, 0x80
	s_addc_u32 s31, s31, 0
	s_add_u32 s10, s34, 0x100
	s_addc_u32 s11, s35, 0
	s_mov_b32 s34, 0

.LBB0_303:
	v_mov_b32_e32 v127, 0
	s_andn2_b64 vcc, exec, s[22:23]
	v_mov_b32_e32 v126, v127
	v_mov_b32_e32 v125, v127
	v_mov_b32_e32 v124, v127
	v_mov_b32_e32 v123, v127
	v_mov_b32_e32 v122, v127
	v_mov_b32_e32 v121, v127
	v_mov_b32_e32 v120, v127
	v_mov_b32_e32 v111, v127
	v_mov_b32_e32 v110, v127
	v_mov_b32_e32 v109, v127
	v_mov_b32_e32 v108, v127
	v_mov_b32_e32 v107, v127
	v_mov_b32_e32 v106, v127
	v_mov_b32_e32 v105, v127
	v_mov_b32_e32 v104, v127
	v_mov_b32_e32 v95, v127
	v_mov_b32_e32 v94, v127
	v_mov_b32_e32 v93, v127
	v_mov_b32_e32 v92, v127
	v_mov_b32_e32 v91, v127
	v_mov_b32_e32 v90, v127
	v_mov_b32_e32 v89, v127
	v_mov_b32_e32 v88, v127
	v_mov_b32_e32 v79, v127
	v_mov_b32_e32 v78, v127
	v_mov_b32_e32 v77, v127
	v_mov_b32_e32 v76, v127
	v_mov_b32_e32 v75, v127
	v_mov_b32_e32 v74, v127
	v_mov_b32_e32 v73, v127
	v_mov_b32_e32 v72, v127
	v_mov_b32_e32 v119, v127
	v_mov_b32_e32 v118, v127
	v_mov_b32_e32 v117, v127
	v_mov_b32_e32 v116, v127
	v_mov_b32_e32 v115, v127
	v_mov_b32_e32 v114, v127
	v_mov_b32_e32 v113, v127
	v_mov_b32_e32 v112, v127
	v_mov_b32_e32 v103, v127
	v_mov_b32_e32 v102, v127
	v_mov_b32_e32 v101, v127
	v_mov_b32_e32 v100, v127
	v_mov_b32_e32 v99, v127
	v_mov_b32_e32 v98, v127
	v_mov_b32_e32 v97, v127
	v_mov_b32_e32 v96, v127
	v_mov_b32_e32 v87, v127
	v_mov_b32_e32 v86, v127
	v_mov_b32_e32 v85, v127
	v_mov_b32_e32 v84, v127
	v_mov_b32_e32 v83, v127
	v_mov_b32_e32 v82, v127
	v_mov_b32_e32 v81, v127
	v_mov_b32_e32 v80, v127
	v_mov_b32_e32 v71, v127
	v_mov_b32_e32 v70, v127
	v_mov_b32_e32 v69, v127
	v_mov_b32_e32 v68, v127
	v_mov_b32_e32 v67, v127
	v_mov_b32_e32 v66, v127
	v_mov_b32_e32 v65, v127
	v_mov_b32_e32 v64, v127
	v_mov_b32_e32 v63, v127
	v_mov_b32_e32 v62, v127
	v_mov_b32_e32 v61, v127
	v_mov_b32_e32 v60, v127
	v_mov_b32_e32 v59, v127
	v_mov_b32_e32 v58, v127
	v_mov_b32_e32 v57, v127
	v_mov_b32_e32 v56, v127
	v_mov_b32_e32 v47, v127
	v_mov_b32_e32 v46, v127
	v_mov_b32_e32 v45, v127
	v_mov_b32_e32 v44, v127
	v_mov_b32_e32 v43, v127
	v_mov_b32_e32 v42, v127
	v_mov_b32_e32 v41, v127
	v_mov_b32_e32 v40, v127
	v_mov_b32_e32 v31, v127
	v_mov_b32_e32 v30, v127
	v_mov_b32_e32 v29, v127
	v_mov_b32_e32 v28, v127
	v_mov_b32_e32 v27, v127
	v_mov_b32_e32 v26, v127
	v_mov_b32_e32 v25, v127
	v_mov_b32_e32 v24, v127
	v_mov_b32_e32 v15, v127
	v_mov_b32_e32 v14, v127
	v_mov_b32_e32 v13, v127
	v_mov_b32_e32 v12, v127
	v_mov_b32_e32 v11, v127
	v_mov_b32_e32 v10, v127
	v_mov_b32_e32 v9, v127
	v_mov_b32_e32 v8, v127
	v_mov_b32_e32 v55, v127
	v_mov_b32_e32 v54, v127
	v_mov_b32_e32 v53, v127
	v_mov_b32_e32 v52, v127
	v_mov_b32_e32 v51, v127
	v_mov_b32_e32 v50, v127
	v_mov_b32_e32 v49, v127
	v_mov_b32_e32 v48, v127
	v_mov_b32_e32 v39, v127
	v_mov_b32_e32 v38, v127
	v_mov_b32_e32 v37, v127
	v_mov_b32_e32 v36, v127
	v_mov_b32_e32 v35, v127
	v_mov_b32_e32 v34, v127
	v_mov_b32_e32 v33, v127
	v_mov_b32_e32 v32, v127
	v_mov_b32_e32 v23, v127
	v_mov_b32_e32 v22, v127
	v_mov_b32_e32 v21, v127
	v_mov_b32_e32 v20, v127
	v_mov_b32_e32 v19, v127
	v_mov_b32_e32 v18, v127
	v_mov_b32_e32 v17, v127
	v_mov_b32_e32 v16, v127
	v_mov_b32_e32 v7, v127
	v_mov_b32_e32 v6, v127
	v_mov_b32_e32 v5, v127
	v_mov_b32_e32 v4, v127
	v_mov_b32_e32 v3, v127
	v_mov_b32_e32 v2, v127
	s_waitcnt lgkmcnt(0)
	v_mov_b32_e32 v1, v127
	v_mov_b32_e32 v0, v127
	s_cbranch_vccnz .LBB0_306
	s_add_u32 s30, s30, 0x80
	s_addc_u32 s31, s31, 0
	s_add_u32 s10, s34, 0x100
	s_addc_u32 s11, s35, 0
	s_mov_b32 s34, 0

.LBB0_392:
	v_mov_b32_e32 v123, 0
	s_andn2_b64 vcc, exec, s[20:21]
	v_mov_b32_e32 v122, v123
	v_mov_b32_e32 v121, v123
	v_mov_b32_e32 v120, v123
	v_mov_b32_e32 v119, v123
	v_mov_b32_e32 v118, v123
	v_mov_b32_e32 v117, v123
	v_mov_b32_e32 v116, v123
	v_mov_b32_e32 v111, v123
	v_mov_b32_e32 v110, v123
	v_mov_b32_e32 v109, v123
	v_mov_b32_e32 v108, v123
	v_mov_b32_e32 v103, v123
	v_mov_b32_e32 v102, v123
	v_mov_b32_e32 v101, v123
	v_mov_b32_e32 v100, v123
	v_mov_b32_e32 v95, v123
	v_mov_b32_e32 v94, v123
	v_mov_b32_e32 v93, v123
	v_mov_b32_e32 v92, v123
	v_mov_b32_e32 v87, v123
	v_mov_b32_e32 v86, v123
	v_mov_b32_e32 v85, v123
	v_mov_b32_e32 v84, v123
	v_mov_b32_e32 v79, v123
	v_mov_b32_e32 v78, v123
	v_mov_b32_e32 v77, v123
	v_mov_b32_e32 v76, v123
	v_mov_b32_e32 v71, v123
	v_mov_b32_e32 v70, v123
	v_mov_b32_e32 v69, v123
	v_mov_b32_e32 v68, v123
	v_mov_b32_e32 v127, v123
	v_mov_b32_e32 v126, v123
	v_mov_b32_e32 v125, v123
	v_mov_b32_e32 v124, v123
	v_mov_b32_e32 v115, v123
	v_mov_b32_e32 v114, v123
	v_mov_b32_e32 v113, v123
	v_mov_b32_e32 v112, v123
	v_mov_b32_e32 v107, v123
	v_mov_b32_e32 v106, v123
	v_mov_b32_e32 v105, v123
	v_mov_b32_e32 v104, v123
	v_mov_b32_e32 v99, v123
	v_mov_b32_e32 v98, v123
	v_mov_b32_e32 v97, v123
	v_mov_b32_e32 v96, v123
	v_mov_b32_e32 v91, v123
	v_mov_b32_e32 v90, v123
	v_mov_b32_e32 v89, v123
	v_mov_b32_e32 v88, v123
	v_mov_b32_e32 v83, v123
	v_mov_b32_e32 v82, v123
	v_mov_b32_e32 v81, v123
	v_mov_b32_e32 v80, v123
	v_mov_b32_e32 v75, v123
	v_mov_b32_e32 v74, v123
	v_mov_b32_e32 v73, v123
	v_mov_b32_e32 v72, v123
	v_mov_b32_e32 v67, v123
	v_mov_b32_e32 v66, v123
	v_mov_b32_e32 v65, v123
	v_mov_b32_e32 v64, v123
	v_mov_b32_e32 v63, v123
	v_mov_b32_e32 v62, v123
	v_mov_b32_e32 v61, v123
	v_mov_b32_e32 v60, v123
	v_mov_b32_e32 v55, v123
	v_mov_b32_e32 v54, v123
	v_mov_b32_e32 v53, v123
	v_mov_b32_e32 v52, v123
	v_mov_b32_e32 v47, v123
	v_mov_b32_e32 v46, v123
	v_mov_b32_e32 v45, v123
	v_mov_b32_e32 v44, v123
	v_mov_b32_e32 v39, v123
	v_mov_b32_e32 v38, v123
	v_mov_b32_e32 v37, v123
	v_mov_b32_e32 v36, v123
	v_mov_b32_e32 v31, v123
	v_mov_b32_e32 v30, v123
	v_mov_b32_e32 v29, v123
	v_mov_b32_e32 v28, v123
	v_mov_b32_e32 v23, v123
	v_mov_b32_e32 v22, v123
	v_mov_b32_e32 v21, v123
	v_mov_b32_e32 v20, v123
	v_mov_b32_e32 v15, v123
	v_mov_b32_e32 v14, v123
	v_mov_b32_e32 v13, v123
	v_mov_b32_e32 v12, v123
	v_mov_b32_e32 v7, v123
	v_mov_b32_e32 v6, v123
	v_mov_b32_e32 v5, v123
	v_mov_b32_e32 v4, v123
	v_mov_b32_e32 v59, v123
	v_mov_b32_e32 v58, v123
	v_mov_b32_e32 v57, v123
	v_mov_b32_e32 v56, v123
	v_mov_b32_e32 v51, v123
	v_mov_b32_e32 v50, v123
	v_mov_b32_e32 v49, v123
	v_mov_b32_e32 v48, v123
	v_mov_b32_e32 v43, v123
	v_mov_b32_e32 v42, v123
	v_mov_b32_e32 v41, v123
	v_mov_b32_e32 v40, v123
	v_mov_b32_e32 v35, v123
	v_mov_b32_e32 v34, v123
	v_mov_b32_e32 v33, v123
	v_mov_b32_e32 v32, v123
	v_mov_b32_e32 v27, v123
	v_mov_b32_e32 v26, v123
	v_mov_b32_e32 v25, v123
	v_mov_b32_e32 v24, v123
	v_mov_b32_e32 v19, v123
	v_mov_b32_e32 v18, v123
	v_mov_b32_e32 v17, v123
	v_mov_b32_e32 v16, v123
	v_mov_b32_e32 v11, v123
	v_mov_b32_e32 v10, v123
	v_mov_b32_e32 v9, v123
	v_mov_b32_e32 v8, v123
	v_mov_b32_e32 v3, v123
	v_mov_b32_e32 v2, v123
	v_mov_b32_e32 v1, v123
	v_mov_b32_e32 v0, v123
	s_cbranch_vccnz .LBB0_395
	s_add_u32 s28, s28, 0x80
	s_addc_u32 s29, s29, 0
	s_add_u32 s10, s30, 0x100
	s_addc_u32 s11, s31, 0
	s_mov_b32 s30, 0

.LBB0_473:
	v_mov_b32_e32 v123, 0
	s_andn2_b64 vcc, exec, s[20:21]
	v_mov_b32_e32 v122, v123
	v_mov_b32_e32 v121, v123
	v_mov_b32_e32 v120, v123
	v_mov_b32_e32 v127, v123
	v_mov_b32_e32 v126, v123
	v_mov_b32_e32 v125, v123
	v_mov_b32_e32 v124, v123
	v_mov_b32_e32 v111, v123
	v_mov_b32_e32 v110, v123
	v_mov_b32_e32 v109, v123
	v_mov_b32_e32 v108, v123
	v_mov_b32_e32 v107, v123
	v_mov_b32_e32 v106, v123
	v_mov_b32_e32 v105, v123
	v_mov_b32_e32 v104, v123
	v_mov_b32_e32 v95, v123
	v_mov_b32_e32 v94, v123
	v_mov_b32_e32 v93, v123
	v_mov_b32_e32 v92, v123
	v_mov_b32_e32 v91, v123
	v_mov_b32_e32 v90, v123
	v_mov_b32_e32 v89, v123
	v_mov_b32_e32 v88, v123
	v_mov_b32_e32 v79, v123
	v_mov_b32_e32 v78, v123
	v_mov_b32_e32 v77, v123
	v_mov_b32_e32 v76, v123
	v_mov_b32_e32 v75, v123
	v_mov_b32_e32 v74, v123
	v_mov_b32_e32 v73, v123
	v_mov_b32_e32 v72, v123
	v_mov_b32_e32 v119, v123
	v_mov_b32_e32 v118, v123
	v_mov_b32_e32 v117, v123
	v_mov_b32_e32 v116, v123
	v_mov_b32_e32 v115, v123
	v_mov_b32_e32 v114, v123
	v_mov_b32_e32 v113, v123
	v_mov_b32_e32 v112, v123
	v_mov_b32_e32 v103, v123
	v_mov_b32_e32 v102, v123
	v_mov_b32_e32 v101, v123
	v_mov_b32_e32 v100, v123
	v_mov_b32_e32 v99, v123
	v_mov_b32_e32 v98, v123
	v_mov_b32_e32 v97, v123
	v_mov_b32_e32 v96, v123
	v_mov_b32_e32 v87, v123
	v_mov_b32_e32 v86, v123
	v_mov_b32_e32 v85, v123
	v_mov_b32_e32 v84, v123
	v_mov_b32_e32 v83, v123
	v_mov_b32_e32 v82, v123
	v_mov_b32_e32 v81, v123
	v_mov_b32_e32 v80, v123
	v_mov_b32_e32 v71, v123
	v_mov_b32_e32 v70, v123
	v_mov_b32_e32 v69, v123
	v_mov_b32_e32 v68, v123
	v_mov_b32_e32 v67, v123
	v_mov_b32_e32 v66, v123
	v_mov_b32_e32 v65, v123
	v_mov_b32_e32 v64, v123
	v_mov_b32_e32 v63, v123
	v_mov_b32_e32 v62, v123
	v_mov_b32_e32 v61, v123
	v_mov_b32_e32 v60, v123
	v_mov_b32_e32 v59, v123
	v_mov_b32_e32 v58, v123
	v_mov_b32_e32 v57, v123
	v_mov_b32_e32 v56, v123
	v_mov_b32_e32 v47, v123
	v_mov_b32_e32 v46, v123
	v_mov_b32_e32 v45, v123
	v_mov_b32_e32 v44, v123
	v_mov_b32_e32 v43, v123
	v_mov_b32_e32 v42, v123
	v_mov_b32_e32 v41, v123
	v_mov_b32_e32 v40, v123
	v_mov_b32_e32 v31, v123
	v_mov_b32_e32 v30, v123
	v_mov_b32_e32 v29, v123
	v_mov_b32_e32 v28, v123
	v_mov_b32_e32 v27, v123
	v_mov_b32_e32 v26, v123
	v_mov_b32_e32 v25, v123
	v_mov_b32_e32 v24, v123
	v_mov_b32_e32 v15, v123
	v_mov_b32_e32 v14, v123
	v_mov_b32_e32 v13, v123
	v_mov_b32_e32 v12, v123
	v_mov_b32_e32 v11, v123
	v_mov_b32_e32 v10, v123
	v_mov_b32_e32 v9, v123
	v_mov_b32_e32 v8, v123
	v_mov_b32_e32 v55, v123
	v_mov_b32_e32 v54, v123
	v_mov_b32_e32 v53, v123
	v_mov_b32_e32 v52, v123
	v_mov_b32_e32 v51, v123
	v_mov_b32_e32 v50, v123
	v_mov_b32_e32 v49, v123
	v_mov_b32_e32 v48, v123
	v_mov_b32_e32 v39, v123
	v_mov_b32_e32 v38, v123
	v_mov_b32_e32 v37, v123
	v_mov_b32_e32 v36, v123
	v_mov_b32_e32 v35, v123
	v_mov_b32_e32 v34, v123
	v_mov_b32_e32 v33, v123
	v_mov_b32_e32 v32, v123
	v_mov_b32_e32 v23, v123
	v_mov_b32_e32 v22, v123
	v_mov_b32_e32 v21, v123
	v_mov_b32_e32 v20, v123
	v_mov_b32_e32 v19, v123
	v_mov_b32_e32 v18, v123
	v_mov_b32_e32 v17, v123
	v_mov_b32_e32 v16, v123
	v_mov_b32_e32 v7, v123
	v_mov_b32_e32 v6, v123
	v_mov_b32_e32 v5, v123
	v_mov_b32_e32 v4, v123
	v_mov_b32_e32 v3, v123
	v_mov_b32_e32 v2, v123
	s_waitcnt lgkmcnt(0)
	v_mov_b32_e32 v1, v123
	v_mov_b32_e32 v0, v123
	s_cbranch_vccnz .LBB0_476
	s_add_u32 s28, s28, 0x80
	s_addc_u32 s29, s29, 0
	s_add_u32 s10, s30, 0x100
	s_addc_u32 s11, s31, 0
	s_mov_b32 s30, 0

.LBB0_574:
	v_mov_b32_e32 v127, 0
	s_andn2_b64 vcc, exec, s[36:37]
	v_mov_b32_e32 v126, v127
	v_mov_b32_e32 v125, v127
	v_mov_b32_e32 v124, v127
	v_mov_b32_e32 v123, v127
	v_mov_b32_e32 v122, v127
	v_mov_b32_e32 v121, v127
	v_mov_b32_e32 v120, v127
	v_mov_b32_e32 v111, v127
	v_mov_b32_e32 v110, v127
	v_mov_b32_e32 v109, v127
	v_mov_b32_e32 v108, v127
	v_mov_b32_e32 v107, v127
	v_mov_b32_e32 v106, v127
	v_mov_b32_e32 v105, v127
	v_mov_b32_e32 v104, v127
	v_mov_b32_e32 v95, v127
	v_mov_b32_e32 v94, v127
	v_mov_b32_e32 v93, v127
	v_mov_b32_e32 v92, v127
	v_mov_b32_e32 v91, v127
	v_mov_b32_e32 v90, v127
	v_mov_b32_e32 v89, v127
	v_mov_b32_e32 v88, v127
	v_mov_b32_e32 v79, v127
	v_mov_b32_e32 v78, v127
	v_mov_b32_e32 v77, v127
	v_mov_b32_e32 v76, v127
	v_mov_b32_e32 v75, v127
	v_mov_b32_e32 v74, v127
	v_mov_b32_e32 v73, v127
	v_mov_b32_e32 v72, v127
	v_mov_b32_e32 v119, v127
	v_mov_b32_e32 v118, v127
	v_mov_b32_e32 v117, v127
	v_mov_b32_e32 v116, v127
	v_mov_b32_e32 v115, v127
	v_mov_b32_e32 v114, v127
	v_mov_b32_e32 v113, v127
	v_mov_b32_e32 v112, v127
	v_mov_b32_e32 v103, v127
	v_mov_b32_e32 v102, v127
	v_mov_b32_e32 v101, v127
	v_mov_b32_e32 v100, v127
	v_mov_b32_e32 v99, v127
	v_mov_b32_e32 v98, v127
	v_mov_b32_e32 v97, v127
	v_mov_b32_e32 v96, v127
	v_mov_b32_e32 v87, v127
	v_mov_b32_e32 v86, v127
	v_mov_b32_e32 v85, v127
	v_mov_b32_e32 v84, v127
	v_mov_b32_e32 v83, v127
	v_mov_b32_e32 v82, v127
	v_mov_b32_e32 v81, v127
	v_mov_b32_e32 v80, v127
	v_mov_b32_e32 v71, v127
	v_mov_b32_e32 v70, v127
	v_mov_b32_e32 v69, v127
	v_mov_b32_e32 v68, v127
	v_mov_b32_e32 v67, v127
	v_mov_b32_e32 v66, v127
	v_mov_b32_e32 v65, v127
	v_mov_b32_e32 v64, v127
	v_mov_b32_e32 v63, v127
	v_mov_b32_e32 v62, v127
	v_mov_b32_e32 v61, v127
	v_mov_b32_e32 v60, v127
	v_mov_b32_e32 v59, v127
	v_mov_b32_e32 v58, v127
	v_mov_b32_e32 v57, v127
	v_mov_b32_e32 v56, v127
	v_mov_b32_e32 v47, v127
	v_mov_b32_e32 v46, v127
	v_mov_b32_e32 v45, v127
	v_mov_b32_e32 v44, v127
	v_mov_b32_e32 v43, v127
	v_mov_b32_e32 v42, v127
	v_mov_b32_e32 v41, v127
	v_mov_b32_e32 v40, v127
	v_mov_b32_e32 v31, v127
	v_mov_b32_e32 v30, v127
	v_mov_b32_e32 v29, v127
	v_mov_b32_e32 v28, v127
	v_mov_b32_e32 v27, v127
	v_mov_b32_e32 v26, v127
	v_mov_b32_e32 v25, v127
	v_mov_b32_e32 v24, v127
	v_mov_b32_e32 v15, v127
	v_mov_b32_e32 v14, v127
	v_mov_b32_e32 v13, v127
	v_mov_b32_e32 v12, v127
	v_mov_b32_e32 v11, v127
	v_mov_b32_e32 v10, v127
	v_mov_b32_e32 v9, v127
	v_mov_b32_e32 v8, v127
	v_mov_b32_e32 v55, v127
	v_mov_b32_e32 v54, v127
	v_mov_b32_e32 v53, v127
	v_mov_b32_e32 v52, v127
	v_mov_b32_e32 v51, v127
	v_mov_b32_e32 v50, v127
	v_mov_b32_e32 v49, v127
	v_mov_b32_e32 v48, v127
	v_mov_b32_e32 v39, v127
	v_mov_b32_e32 v38, v127
	v_mov_b32_e32 v37, v127
	v_mov_b32_e32 v36, v127
	v_mov_b32_e32 v35, v127
	v_mov_b32_e32 v34, v127
	v_mov_b32_e32 v33, v127
	v_mov_b32_e32 v32, v127
	v_mov_b32_e32 v23, v127
	v_mov_b32_e32 v22, v127
	v_mov_b32_e32 v21, v127
	v_mov_b32_e32 v20, v127
	v_mov_b32_e32 v19, v127
	v_mov_b32_e32 v18, v127
	v_mov_b32_e32 v17, v127
	v_mov_b32_e32 v16, v127
	v_mov_b32_e32 v7, v127
	v_mov_b32_e32 v6, v127
	v_mov_b32_e32 v5, v127
	v_mov_b32_e32 v4, v127
	v_mov_b32_e32 v3, v127
	v_mov_b32_e32 v2, v127
	v_mov_b32_e32 v1, v127
	v_mov_b32_e32 v0, v127
	s_cbranch_vccnz .LBB0_577
	s_add_u32 s0, s0, 0x80
	s_addc_u32 s1, s1, 0
	s_add_u32 s38, s38, 0x100
	s_addc_u32 s39, s39, 0
	s_mov_b32 s16, 0

.LBB0_796:
	v_mov_b32_e32 v127, 0
	s_andn2_b64 vcc, exec, s[20:21]
	v_mov_b32_e32 v126, v127
	v_mov_b32_e32 v125, v127
	v_mov_b32_e32 v124, v127
	v_mov_b32_e32 v123, v127
	v_mov_b32_e32 v122, v127
	v_mov_b32_e32 v121, v127
	v_mov_b32_e32 v120, v127
	v_mov_b32_e32 v111, v127
	v_mov_b32_e32 v110, v127
	v_mov_b32_e32 v109, v127
	v_mov_b32_e32 v108, v127
	v_mov_b32_e32 v107, v127
	v_mov_b32_e32 v106, v127
	v_mov_b32_e32 v105, v127
	v_mov_b32_e32 v104, v127
	v_mov_b32_e32 v95, v127
	v_mov_b32_e32 v94, v127
	v_mov_b32_e32 v93, v127
	v_mov_b32_e32 v92, v127
	v_mov_b32_e32 v91, v127
	v_mov_b32_e32 v90, v127
	v_mov_b32_e32 v89, v127
	v_mov_b32_e32 v88, v127
	v_mov_b32_e32 v79, v127
	v_mov_b32_e32 v78, v127
	v_mov_b32_e32 v77, v127
	v_mov_b32_e32 v76, v127
	v_mov_b32_e32 v75, v127
	v_mov_b32_e32 v74, v127
	v_mov_b32_e32 v73, v127
	v_mov_b32_e32 v72, v127
	v_mov_b32_e32 v119, v127
	v_mov_b32_e32 v118, v127
	v_mov_b32_e32 v117, v127
	v_mov_b32_e32 v116, v127
	v_mov_b32_e32 v115, v127
	v_mov_b32_e32 v114, v127
	v_mov_b32_e32 v113, v127
	v_mov_b32_e32 v112, v127
	v_mov_b32_e32 v103, v127
	v_mov_b32_e32 v102, v127
	v_mov_b32_e32 v101, v127
	v_mov_b32_e32 v100, v127
	v_mov_b32_e32 v99, v127
	v_mov_b32_e32 v98, v127
	v_mov_b32_e32 v97, v127
	v_mov_b32_e32 v96, v127
	v_mov_b32_e32 v87, v127
	v_mov_b32_e32 v86, v127
	v_mov_b32_e32 v85, v127
	v_mov_b32_e32 v84, v127
	v_mov_b32_e32 v83, v127
	v_mov_b32_e32 v82, v127
	v_mov_b32_e32 v81, v127
	v_mov_b32_e32 v80, v127
	v_mov_b32_e32 v71, v127
	v_mov_b32_e32 v70, v127
	v_mov_b32_e32 v69, v127
	v_mov_b32_e32 v68, v127
	v_mov_b32_e32 v67, v127
	v_mov_b32_e32 v66, v127
	v_mov_b32_e32 v65, v127
	v_mov_b32_e32 v64, v127
	v_mov_b32_e32 v63, v127
	v_mov_b32_e32 v62, v127
	v_mov_b32_e32 v61, v127
	v_mov_b32_e32 v60, v127
	v_mov_b32_e32 v59, v127
	v_mov_b32_e32 v58, v127
	v_mov_b32_e32 v57, v127
	v_mov_b32_e32 v56, v127
	v_mov_b32_e32 v47, v127
	v_mov_b32_e32 v46, v127
	v_mov_b32_e32 v45, v127
	v_mov_b32_e32 v44, v127
	v_mov_b32_e32 v43, v127
	v_mov_b32_e32 v42, v127
	v_mov_b32_e32 v41, v127
	v_mov_b32_e32 v40, v127
	v_mov_b32_e32 v31, v127
	v_mov_b32_e32 v30, v127
	v_mov_b32_e32 v29, v127
	v_mov_b32_e32 v28, v127
	v_mov_b32_e32 v27, v127
	v_mov_b32_e32 v26, v127
	v_mov_b32_e32 v25, v127
	v_mov_b32_e32 v24, v127
	v_mov_b32_e32 v15, v127
	v_mov_b32_e32 v14, v127
	v_mov_b32_e32 v13, v127
	v_mov_b32_e32 v12, v127
	v_mov_b32_e32 v11, v127
	v_mov_b32_e32 v10, v127
	v_mov_b32_e32 v9, v127
	v_mov_b32_e32 v8, v127
	v_mov_b32_e32 v55, v127
	v_mov_b32_e32 v54, v127
	v_mov_b32_e32 v53, v127
	v_mov_b32_e32 v52, v127
	v_mov_b32_e32 v51, v127
	v_mov_b32_e32 v50, v127
	v_mov_b32_e32 v49, v127
	v_mov_b32_e32 v48, v127
	v_mov_b32_e32 v39, v127
	v_mov_b32_e32 v38, v127
	v_mov_b32_e32 v37, v127
	v_mov_b32_e32 v36, v127
	v_mov_b32_e32 v35, v127
	v_mov_b32_e32 v34, v127
	v_mov_b32_e32 v33, v127
	v_mov_b32_e32 v32, v127
	v_mov_b32_e32 v23, v127
	v_mov_b32_e32 v22, v127
	v_mov_b32_e32 v21, v127
	v_mov_b32_e32 v20, v127
	v_mov_b32_e32 v19, v127
	v_mov_b32_e32 v18, v127
	v_mov_b32_e32 v17, v127
	v_mov_b32_e32 v16, v127
	v_mov_b32_e32 v7, v127
	v_mov_b32_e32 v6, v127
	v_mov_b32_e32 v5, v127
	v_mov_b32_e32 v4, v127
	v_mov_b32_e32 v3, v127
	v_mov_b32_e32 v2, v127
	v_mov_b32_e32 v1, v127
	v_mov_b32_e32 v0, v127
	s_cbranch_vccnz .LBB0_799
	s_add_u32 s28, s16, 0x80
	s_addc_u32 s29, s17, 0
	s_add_u32 s10, s30, 0x100
	s_addc_u32 s11, s31, 0
	s_mov_b32 s16, 0

.LBB0_821:
	v_mov_b32_e32 v123, 0
	s_andn2_b64 vcc, exec, s[18:19]
	v_mov_b32_e32 v122, v123
	v_mov_b32_e32 v121, v123
	v_mov_b32_e32 v120, v123
	v_mov_b32_e32 v127, v123
	v_mov_b32_e32 v126, v123
	v_mov_b32_e32 v125, v123
	v_mov_b32_e32 v124, v123
	v_mov_b32_e32 v119, v123
	v_mov_b32_e32 v118, v123
	v_mov_b32_e32 v117, v123
	v_mov_b32_e32 v116, v123
	v_mov_b32_e32 v115, v123
	v_mov_b32_e32 v114, v123
	v_mov_b32_e32 v113, v123
	v_mov_b32_e32 v112, v123
	v_mov_b32_e32 v111, v123
	v_mov_b32_e32 v110, v123
	v_mov_b32_e32 v109, v123
	v_mov_b32_e32 v108, v123
	v_mov_b32_e32 v107, v123
	v_mov_b32_e32 v106, v123
	v_mov_b32_e32 v105, v123
	v_mov_b32_e32 v104, v123
	v_mov_b32_e32 v103, v123
	v_mov_b32_e32 v102, v123
	v_mov_b32_e32 v101, v123
	v_mov_b32_e32 v100, v123
	v_mov_b32_e32 v99, v123
	v_mov_b32_e32 v98, v123
	v_mov_b32_e32 v97, v123
	v_mov_b32_e32 v96, v123
	v_mov_b32_e32 v63, v123
	v_mov_b32_e32 v62, v123
	v_mov_b32_e32 v61, v123
	v_mov_b32_e32 v60, v123
	v_mov_b32_e32 v59, v123
	v_mov_b32_e32 v58, v123
	v_mov_b32_e32 v57, v123
	v_mov_b32_e32 v56, v123
	v_mov_b32_e32 v55, v123
	v_mov_b32_e32 v54, v123
	v_mov_b32_e32 v53, v123
	v_mov_b32_e32 v52, v123
	v_mov_b32_e32 v51, v123
	v_mov_b32_e32 v50, v123
	v_mov_b32_e32 v49, v123
	v_mov_b32_e32 v48, v123
	v_mov_b32_e32 v47, v123
	v_mov_b32_e32 v46, v123
	v_mov_b32_e32 v45, v123
	v_mov_b32_e32 v44, v123
	v_mov_b32_e32 v43, v123
	v_mov_b32_e32 v42, v123
	v_mov_b32_e32 v41, v123
	v_mov_b32_e32 v40, v123
	v_mov_b32_e32 v39, v123
	v_mov_b32_e32 v38, v123
	v_mov_b32_e32 v37, v123
	v_mov_b32_e32 v36, v123
	v_mov_b32_e32 v35, v123
	v_mov_b32_e32 v34, v123
	v_mov_b32_e32 v33, v123
	v_mov_b32_e32 v32, v123
	v_mov_b32_e32 v95, v123
	v_mov_b32_e32 v94, v123
	v_mov_b32_e32 v93, v123
	v_mov_b32_e32 v92, v123
	v_mov_b32_e32 v91, v123
	v_mov_b32_e32 v90, v123
	v_mov_b32_e32 v89, v123
	v_mov_b32_e32 v88, v123
	v_mov_b32_e32 v87, v123
	v_mov_b32_e32 v86, v123
	v_mov_b32_e32 v85, v123
	v_mov_b32_e32 v84, v123
	v_mov_b32_e32 v83, v123
	v_mov_b32_e32 v82, v123
	v_mov_b32_e32 v81, v123
	v_mov_b32_e32 v80, v123
	v_mov_b32_e32 v79, v123
	v_mov_b32_e32 v78, v123
	v_mov_b32_e32 v77, v123
	v_mov_b32_e32 v76, v123
	v_mov_b32_e32 v75, v123
	v_mov_b32_e32 v74, v123
	v_mov_b32_e32 v73, v123
	v_mov_b32_e32 v72, v123
	v_mov_b32_e32 v71, v123
	v_mov_b32_e32 v70, v123
	v_mov_b32_e32 v69, v123
	v_mov_b32_e32 v68, v123
	v_mov_b32_e32 v67, v123
	v_mov_b32_e32 v66, v123
	v_mov_b32_e32 v65, v123
	v_mov_b32_e32 v64, v123
	v_mov_b32_e32 v31, v123
	v_mov_b32_e32 v30, v123
	v_mov_b32_e32 v29, v123
	v_mov_b32_e32 v28, v123
	v_mov_b32_e32 v27, v123
	v_mov_b32_e32 v26, v123
	v_mov_b32_e32 v25, v123
	v_mov_b32_e32 v24, v123
	v_mov_b32_e32 v23, v123
	v_mov_b32_e32 v22, v123
	v_mov_b32_e32 v21, v123
	v_mov_b32_e32 v20, v123
	v_mov_b32_e32 v19, v123
	v_mov_b32_e32 v18, v123
	v_mov_b32_e32 v17, v123
	v_mov_b32_e32 v16, v123
	v_mov_b32_e32 v15, v123
	v_mov_b32_e32 v14, v123
	v_mov_b32_e32 v13, v123
	v_mov_b32_e32 v12, v123
	v_mov_b32_e32 v11, v123
	v_mov_b32_e32 v10, v123
	v_mov_b32_e32 v9, v123
	v_mov_b32_e32 v8, v123
	v_mov_b32_e32 v7, v123
	v_mov_b32_e32 v6, v123
	v_mov_b32_e32 v5, v123
	v_mov_b32_e32 v4, v123
	v_mov_b32_e32 v3, v123
	v_mov_b32_e32 v2, v123
	v_mov_b32_e32 v1, v123
	v_mov_b32_e32 v0, v123
	s_cbranch_vccnz .LBB0_824
	s_add_u32 s26, s26, 0x80
	s_addc_u32 s27, s27, 0
	s_add_u32 s10, s28, 0x100
	s_addc_u32 s11, s29, 0
	s_mov_b32 s16, 0

.LBB0_842:
	v_mov_b32_e32 v127, 0
	s_andn2_b64 vcc, exec, s[22:23]
	v_mov_b32_e32 v126, v127
	v_mov_b32_e32 v125, v127
	v_mov_b32_e32 v124, v127
	v_mov_b32_e32 v123, v127
	v_mov_b32_e32 v122, v127
	v_mov_b32_e32 v121, v127
	v_mov_b32_e32 v120, v127
	v_mov_b32_e32 v111, v127
	v_mov_b32_e32 v110, v127
	v_mov_b32_e32 v109, v127
	v_mov_b32_e32 v108, v127
	v_mov_b32_e32 v107, v127
	v_mov_b32_e32 v106, v127
	v_mov_b32_e32 v105, v127
	v_mov_b32_e32 v104, v127
	v_mov_b32_e32 v95, v127
	v_mov_b32_e32 v94, v127
	v_mov_b32_e32 v93, v127
	v_mov_b32_e32 v92, v127
	v_mov_b32_e32 v91, v127
	v_mov_b32_e32 v90, v127
	v_mov_b32_e32 v89, v127
	v_mov_b32_e32 v88, v127
	v_mov_b32_e32 v79, v127
	v_mov_b32_e32 v78, v127
	v_mov_b32_e32 v77, v127
	v_mov_b32_e32 v76, v127
	v_mov_b32_e32 v75, v127
	v_mov_b32_e32 v74, v127
	v_mov_b32_e32 v73, v127
	v_mov_b32_e32 v72, v127
	v_mov_b32_e32 v119, v127
	v_mov_b32_e32 v118, v127
	v_mov_b32_e32 v117, v127
	v_mov_b32_e32 v116, v127
	v_mov_b32_e32 v115, v127
	v_mov_b32_e32 v114, v127
	v_mov_b32_e32 v113, v127
	v_mov_b32_e32 v112, v127
	v_mov_b32_e32 v103, v127
	v_mov_b32_e32 v102, v127
	v_mov_b32_e32 v101, v127
	v_mov_b32_e32 v100, v127
	v_mov_b32_e32 v99, v127
	v_mov_b32_e32 v98, v127
	v_mov_b32_e32 v97, v127
	v_mov_b32_e32 v96, v127
	v_mov_b32_e32 v87, v127
	v_mov_b32_e32 v86, v127
	v_mov_b32_e32 v85, v127
	v_mov_b32_e32 v84, v127
	v_mov_b32_e32 v83, v127
	v_mov_b32_e32 v82, v127
	v_mov_b32_e32 v81, v127
	v_mov_b32_e32 v80, v127
	v_mov_b32_e32 v71, v127
	v_mov_b32_e32 v70, v127
	v_mov_b32_e32 v69, v127
	v_mov_b32_e32 v68, v127
	v_mov_b32_e32 v67, v127
	v_mov_b32_e32 v66, v127
	v_mov_b32_e32 v65, v127
	v_mov_b32_e32 v64, v127
	v_mov_b32_e32 v63, v127
	v_mov_b32_e32 v62, v127
	v_mov_b32_e32 v61, v127
	v_mov_b32_e32 v60, v127
	v_mov_b32_e32 v59, v127
	v_mov_b32_e32 v58, v127
	v_mov_b32_e32 v57, v127
	v_mov_b32_e32 v56, v127
	v_mov_b32_e32 v47, v127
	v_mov_b32_e32 v46, v127
	v_mov_b32_e32 v45, v127
	v_mov_b32_e32 v44, v127
	v_mov_b32_e32 v43, v127
	v_mov_b32_e32 v42, v127
	v_mov_b32_e32 v41, v127
	v_mov_b32_e32 v40, v127
	v_mov_b32_e32 v31, v127
	v_mov_b32_e32 v30, v127
	v_mov_b32_e32 v29, v127
	v_mov_b32_e32 v28, v127
	v_mov_b32_e32 v27, v127
	v_mov_b32_e32 v26, v127
	v_mov_b32_e32 v25, v127
	v_mov_b32_e32 v24, v127
	v_mov_b32_e32 v15, v127
	v_mov_b32_e32 v14, v127
	v_mov_b32_e32 v13, v127
	v_mov_b32_e32 v12, v127
	v_mov_b32_e32 v11, v127
	v_mov_b32_e32 v10, v127
	v_mov_b32_e32 v9, v127
	v_mov_b32_e32 v8, v127
	v_mov_b32_e32 v55, v127
	v_mov_b32_e32 v54, v127
	v_mov_b32_e32 v53, v127
	v_mov_b32_e32 v52, v127
	v_mov_b32_e32 v51, v127
	v_mov_b32_e32 v50, v127
	v_mov_b32_e32 v49, v127
	v_mov_b32_e32 v48, v127
	v_mov_b32_e32 v39, v127
	v_mov_b32_e32 v38, v127
	v_mov_b32_e32 v37, v127
	v_mov_b32_e32 v36, v127
	v_mov_b32_e32 v35, v127
	v_mov_b32_e32 v34, v127
	v_mov_b32_e32 v33, v127
	v_mov_b32_e32 v32, v127
	v_mov_b32_e32 v23, v127
	v_mov_b32_e32 v22, v127
	v_mov_b32_e32 v21, v127
	v_mov_b32_e32 v20, v127
	v_mov_b32_e32 v19, v127
	v_mov_b32_e32 v18, v127
	v_mov_b32_e32 v17, v127
	v_mov_b32_e32 v16, v127
	v_mov_b32_e32 v7, v127
	v_mov_b32_e32 v6, v127
	v_mov_b32_e32 v5, v127
	v_mov_b32_e32 v4, v127
	v_mov_b32_e32 v3, v127
	v_mov_b32_e32 v2, v127
	v_mov_b32_e32 v1, v127
	v_mov_b32_e32 v0, v127
	s_cbranch_vccnz .LBB0_845
	s_add_u32 s0, s0, 0x80
	s_addc_u32 s1, s1, 0
	s_add_u32 s10, s30, 0x100
	s_addc_u32 s11, s31, 0
	s_mov_b32 s16, 0

.LBB0_1051:
	v_mov_b32_e32 v123, 0
	s_andn2_b64 vcc, exec, s[20:21]
	v_mov_b32_e32 v122, v123
	v_mov_b32_e32 v121, v123
	v_mov_b32_e32 v120, v123
	v_mov_b32_e32 v127, v123
	v_mov_b32_e32 v126, v123
	v_mov_b32_e32 v125, v123
	v_mov_b32_e32 v124, v123
	v_mov_b32_e32 v111, v123
	v_mov_b32_e32 v110, v123
	v_mov_b32_e32 v109, v123
	v_mov_b32_e32 v108, v123
	v_mov_b32_e32 v107, v123
	v_mov_b32_e32 v106, v123
	v_mov_b32_e32 v105, v123
	v_mov_b32_e32 v104, v123
	v_mov_b32_e32 v95, v123
	v_mov_b32_e32 v94, v123
	v_mov_b32_e32 v93, v123
	v_mov_b32_e32 v92, v123
	v_mov_b32_e32 v91, v123
	v_mov_b32_e32 v90, v123
	v_mov_b32_e32 v89, v123
	v_mov_b32_e32 v88, v123
	v_mov_b32_e32 v79, v123
	v_mov_b32_e32 v78, v123
	v_mov_b32_e32 v77, v123
	v_mov_b32_e32 v76, v123
	v_mov_b32_e32 v75, v123
	v_mov_b32_e32 v74, v123
	v_mov_b32_e32 v73, v123
	v_mov_b32_e32 v72, v123
	v_mov_b32_e32 v119, v123
	v_mov_b32_e32 v118, v123
	v_mov_b32_e32 v117, v123
	v_mov_b32_e32 v116, v123
	v_mov_b32_e32 v115, v123
	v_mov_b32_e32 v114, v123
	v_mov_b32_e32 v113, v123
	v_mov_b32_e32 v112, v123
	v_mov_b32_e32 v103, v123
	v_mov_b32_e32 v102, v123
	v_mov_b32_e32 v101, v123
	v_mov_b32_e32 v100, v123
	v_mov_b32_e32 v99, v123
	v_mov_b32_e32 v98, v123
	v_mov_b32_e32 v97, v123
	v_mov_b32_e32 v96, v123
	v_mov_b32_e32 v87, v123
	v_mov_b32_e32 v86, v123
	v_mov_b32_e32 v85, v123
	v_mov_b32_e32 v84, v123
	v_mov_b32_e32 v83, v123
	v_mov_b32_e32 v82, v123
	v_mov_b32_e32 v81, v123
	v_mov_b32_e32 v80, v123
	v_mov_b32_e32 v71, v123
	v_mov_b32_e32 v70, v123
	v_mov_b32_e32 v69, v123
	v_mov_b32_e32 v68, v123
	v_mov_b32_e32 v67, v123
	v_mov_b32_e32 v66, v123
	v_mov_b32_e32 v65, v123
	v_mov_b32_e32 v64, v123
	v_mov_b32_e32 v63, v123
	v_mov_b32_e32 v62, v123
	v_mov_b32_e32 v61, v123
	v_mov_b32_e32 v60, v123
	v_mov_b32_e32 v59, v123
	v_mov_b32_e32 v58, v123
	v_mov_b32_e32 v57, v123
	v_mov_b32_e32 v56, v123
	v_mov_b32_e32 v47, v123
	v_mov_b32_e32 v46, v123
	v_mov_b32_e32 v45, v123
	v_mov_b32_e32 v44, v123
	v_mov_b32_e32 v43, v123
	v_mov_b32_e32 v42, v123
	v_mov_b32_e32 v41, v123
	v_mov_b32_e32 v40, v123
	v_mov_b32_e32 v31, v123
	v_mov_b32_e32 v30, v123
	v_mov_b32_e32 v29, v123
	v_mov_b32_e32 v28, v123
	v_mov_b32_e32 v27, v123
	v_mov_b32_e32 v26, v123
	v_mov_b32_e32 v25, v123
	v_mov_b32_e32 v24, v123
	v_mov_b32_e32 v15, v123
	v_mov_b32_e32 v14, v123
	v_mov_b32_e32 v13, v123
	v_mov_b32_e32 v12, v123
	v_mov_b32_e32 v11, v123
	v_mov_b32_e32 v10, v123
	v_mov_b32_e32 v9, v123
	v_mov_b32_e32 v8, v123
	v_mov_b32_e32 v55, v123
	v_mov_b32_e32 v54, v123
	v_mov_b32_e32 v53, v123
	v_mov_b32_e32 v52, v123
	v_mov_b32_e32 v51, v123
	v_mov_b32_e32 v50, v123
	v_mov_b32_e32 v49, v123
	v_mov_b32_e32 v48, v123
	v_mov_b32_e32 v39, v123
	v_mov_b32_e32 v38, v123
	v_mov_b32_e32 v37, v123
	v_mov_b32_e32 v36, v123
	v_mov_b32_e32 v35, v123
	v_mov_b32_e32 v34, v123
	v_mov_b32_e32 v33, v123
	v_mov_b32_e32 v32, v123
	v_mov_b32_e32 v23, v123
	v_mov_b32_e32 v22, v123
	v_mov_b32_e32 v21, v123
	v_mov_b32_e32 v20, v123
	v_mov_b32_e32 v19, v123
	v_mov_b32_e32 v18, v123
	v_mov_b32_e32 v17, v123
	v_mov_b32_e32 v16, v123
	v_mov_b32_e32 v7, v123
	v_mov_b32_e32 v6, v123
	v_mov_b32_e32 v5, v123
	v_mov_b32_e32 v4, v123
	v_mov_b32_e32 v3, v123
	v_mov_b32_e32 v2, v123
	s_waitcnt lgkmcnt(0)
	v_mov_b32_e32 v1, v123
	v_mov_b32_e32 v0, v123
	s_cbranch_vccnz .LBB0_1054
	s_add_u32 s28, s28, 0x80
	s_addc_u32 s29, s29, 0
	s_add_u32 s10, s30, 0x100
	s_addc_u32 s11, s31, 0
	s_mov_b32 s16, 0

.LBB0_1222:
	v_mov_b32_e32 v123, 0
	s_andn2_b64 vcc, exec, s[18:19]
	v_mov_b32_e32 v122, v123
	v_mov_b32_e32 v121, v123
	v_mov_b32_e32 v120, v123
	v_mov_b32_e32 v127, v123
	v_mov_b32_e32 v126, v123
	v_mov_b32_e32 v125, v123
	v_mov_b32_e32 v124, v123
	v_mov_b32_e32 v111, v123
	v_mov_b32_e32 v110, v123
	v_mov_b32_e32 v109, v123
	v_mov_b32_e32 v108, v123
	v_mov_b32_e32 v107, v123
	v_mov_b32_e32 v106, v123
	v_mov_b32_e32 v105, v123
	v_mov_b32_e32 v104, v123
	v_mov_b32_e32 v95, v123
	v_mov_b32_e32 v94, v123
	v_mov_b32_e32 v93, v123
	v_mov_b32_e32 v92, v123
	v_mov_b32_e32 v91, v123
	v_mov_b32_e32 v90, v123
	v_mov_b32_e32 v89, v123
	v_mov_b32_e32 v88, v123
	v_mov_b32_e32 v79, v123
	v_mov_b32_e32 v78, v123
	v_mov_b32_e32 v77, v123
	v_mov_b32_e32 v76, v123
	v_mov_b32_e32 v75, v123
	v_mov_b32_e32 v74, v123
	v_mov_b32_e32 v73, v123
	v_mov_b32_e32 v72, v123
	v_mov_b32_e32 v119, v123
	v_mov_b32_e32 v118, v123
	v_mov_b32_e32 v117, v123
	v_mov_b32_e32 v116, v123
	v_mov_b32_e32 v115, v123
	v_mov_b32_e32 v114, v123
	v_mov_b32_e32 v113, v123
	v_mov_b32_e32 v112, v123
	v_mov_b32_e32 v103, v123
	v_mov_b32_e32 v102, v123
	v_mov_b32_e32 v101, v123
	v_mov_b32_e32 v100, v123
	v_mov_b32_e32 v99, v123
	v_mov_b32_e32 v98, v123
	v_mov_b32_e32 v97, v123
	v_mov_b32_e32 v96, v123
	v_mov_b32_e32 v87, v123
	v_mov_b32_e32 v86, v123
	v_mov_b32_e32 v85, v123
	v_mov_b32_e32 v84, v123
	v_mov_b32_e32 v83, v123
	v_mov_b32_e32 v82, v123
	v_mov_b32_e32 v81, v123
	v_mov_b32_e32 v80, v123
	v_mov_b32_e32 v71, v123
	v_mov_b32_e32 v70, v123
	v_mov_b32_e32 v69, v123
	v_mov_b32_e32 v68, v123
	v_mov_b32_e32 v67, v123
	v_mov_b32_e32 v66, v123
	v_mov_b32_e32 v65, v123
	v_mov_b32_e32 v64, v123
	v_mov_b32_e32 v63, v123
	v_mov_b32_e32 v62, v123
	v_mov_b32_e32 v61, v123
	v_mov_b32_e32 v60, v123
	v_mov_b32_e32 v59, v123
	v_mov_b32_e32 v58, v123
	v_mov_b32_e32 v57, v123
	v_mov_b32_e32 v56, v123
	v_mov_b32_e32 v47, v123
	v_mov_b32_e32 v46, v123
	v_mov_b32_e32 v45, v123
	v_mov_b32_e32 v44, v123
	v_mov_b32_e32 v43, v123
	v_mov_b32_e32 v42, v123
	v_mov_b32_e32 v41, v123
	v_mov_b32_e32 v40, v123
	v_mov_b32_e32 v31, v123
	v_mov_b32_e32 v30, v123
	v_mov_b32_e32 v29, v123
	v_mov_b32_e32 v28, v123
	v_mov_b32_e32 v27, v123
	v_mov_b32_e32 v26, v123
	v_mov_b32_e32 v25, v123
	v_mov_b32_e32 v24, v123
	v_mov_b32_e32 v15, v123
	v_mov_b32_e32 v14, v123
	v_mov_b32_e32 v13, v123
	v_mov_b32_e32 v12, v123
	v_mov_b32_e32 v11, v123
	v_mov_b32_e32 v10, v123
	v_mov_b32_e32 v9, v123
	v_mov_b32_e32 v8, v123
	v_mov_b32_e32 v55, v123
	v_mov_b32_e32 v54, v123
	v_mov_b32_e32 v53, v123
	v_mov_b32_e32 v52, v123
	v_mov_b32_e32 v51, v123
	v_mov_b32_e32 v50, v123
	v_mov_b32_e32 v49, v123
	v_mov_b32_e32 v48, v123
	v_mov_b32_e32 v39, v123
	v_mov_b32_e32 v38, v123
	v_mov_b32_e32 v37, v123
	v_mov_b32_e32 v36, v123
	v_mov_b32_e32 v35, v123
	v_mov_b32_e32 v34, v123
	v_mov_b32_e32 v33, v123
	v_mov_b32_e32 v32, v123
	v_mov_b32_e32 v23, v123
	v_mov_b32_e32 v22, v123
	v_mov_b32_e32 v21, v123
	v_mov_b32_e32 v20, v123
	v_mov_b32_e32 v19, v123
	v_mov_b32_e32 v18, v123
	v_mov_b32_e32 v17, v123
	v_mov_b32_e32 v16, v123
	v_mov_b32_e32 v7, v123
	v_mov_b32_e32 v6, v123
	v_mov_b32_e32 v5, v123
	v_mov_b32_e32 v4, v123
	v_mov_b32_e32 v3, v123
	v_mov_b32_e32 v2, v123
	s_waitcnt lgkmcnt(0)
	v_mov_b32_e32 v1, v123
	v_mov_b32_e32 v0, v123
	s_cbranch_vccnz .LBB0_1226
	s_add_u32 s26, s26, 0x80
	s_addc_u32 s27, s27, 0
	s_add_u32 s10, s28, 0x100
	s_addc_u32 s11, s29, 0
	s_mov_b32 s28, 0
